# LRU pass C output stage: carry-in and wave aggregates of a 16-channel group read unconditionally one group ahead, wave-prefix fold applied with fma+cndmask on the same wave-uniform masks instead of ex
# speedup vs baseline: 1.0055x; 1.0027x over previous
; DEVI unsigned pk2(float lo, float hi) { f32x2 v = {lo, hi}; bf16x2_t b = __builtin_convertvector(v, bf16x2_t); return __builtin_bit_cast(unsigned, b); }
; DEVI float bflo(unsigned u) { return __uint_as_float(u << 16); }
; DEVI float bfhi(unsigned u) { return __uint_as_float(u & 0xffff0000u); }
; template <bool PASS_C>
; DEVI void lru_item(const P& p, int item, int next_item, uint4& u0, uint4& u1, uint4& u2, float& cpre, char* smem) {
;     ...
;                 float hh = apre[nn][0] * hw + bpre[nn][0];
; #pragma unroll
;                 for (int j = 0; j < 4; ++j) { hh = av[nn][0][j] * hh + bv[nn][0][j]; y[j] = hh; }
;             }
;             {
;                 float hw = carry[64 + ch];
; #pragma unroll
;     ...
;                     if (ww > w) hw = wagg[((ww * 2 + 1) * 64 + ch) * 2] * hw + wagg[((ww * 2 + 1) * 64 + ch) * 2 + 1];
;                 float hh = apre[nn][1] * hw + bpre[nn][1];
; #pragma unroll
;                 for (int j = 3; j >= 0; --j) { hh = av[nn][1][j] * hh + bv[nn][1][j]; y[j] += hh; }
;             }
; #pragma unroll
;             for (int j = 0; j < 4; ++j) ytile[(16 * w + 4 * fq + j) * 66 + ch] = y[j];
;         }
;         __syncthreads();
;         {
;             const int tok = tid >> 2, cg0 = (tid & 3) * 16;
;             bf16_t* MX = (bf16_t*)(p.ws + OFF_A) + (rbase + tb + tok) * 1024 + h * 64 + cg0;
; #pragma unroll
;             for (int i = 0; i < 2; ++i) {
;                 const uint4 s = i ? sg1 : sg0;
;                 const float* yy = ytile + tok * 66 + cg0 + 8 * i;
;                 uint4 o;
;                 o.x = pk2(yy[0] * bflo(s.x), yy[1] * bfhi(s.x)); o.y = pk2(yy[2] * bflo(s.y), yy[3] * bfhi(s.y));
;                 o.z = pk2(yy[4] * bflo(s.z), yy[5] * bfhi(s.z)); o.w = pk2(yy[6] * bflo(s.w), yy[7] * bfhi(s.w));
;                 *(uint4*)(MX + 8 * i) = o;
;             }
;         }
.LBB0_720:
	s_or_b64 exec, exec, s[28:29]
	v_cndmask_b32_e64 v40, 1.0, v198, s[12:13]
	v_cndmask_b32_e64 v41, 0, v200, s[12:13]
	v_cndmask_b32_e64 v40, v40, v204, s[14:15]
	v_cndmask_b32_e64 v41, v41, v202, s[14:15]
	v_cndmask_b32_e64 v40, v40, v205, s[16:17]
	v_cndmask_b32_e64 v41, v41, v203, s[16:17]
	v_fmac_f32_e32 v41, v40, v38
	v_fmac_f32_e32 v30, v34, v41
	v_fmac_f32_e32 v32, v31, v30
	v_fmac_f32_e32 v35, v33, v32
	v_cndmask_b32_e64 v31, 0, v209, s[14:15]
	v_cndmask_b32_e64 v33, 1.0, v206, s[14:15]
	v_cndmask_b32_e64 v31, v31, v208, s[12:13]
	v_cndmask_b32_e64 v33, v33, v210, s[12:13]
	v_cndmask_b32_e64 v31, v31, v207, s[10:11]
	v_cndmask_b32_e64 v33, v33, v211, s[10:11]
	v_fmac_f32_e32 v31, v33, v39
	v_fmac_f32_e32 v29, v27, v31
	v_fmac_f32_e32 v28, v24, v29
	v_fmac_f32_e32 v25, v23, v28
	v_fmac_f32_e32 v26, v22, v25
	v_fmac_f32_e32 v36, v37, v35
	v_add_f32_e32 v23, v32, v25
	v_add_f32_e32 v22, v30, v26
	v_add_f32_e32 v27, v36, v29
	v_add_f32_e32 v24, v35, v28
	ds_write2_b32 v70, v22, v23 offset0:48 offset1:114
	ds_write2_b32 v70, v24, v27 offset0:180 offset1:246
	v_lshl_add_u64 v[22:23], v[106:107], 1, s[90:91]
	v_lshl_add_u64 v[22:23], v[22:23], 0, s[0:1]
	v_lshl_add_u64 v[30:31], v[22:23], 0, v[78:79]
	v_add_u32_e32 v22, 0x8c00, v124
	s_waitcnt lgkmcnt(0)
	s_barrier
	ds_read2_b64 v[22:25], v22 offset1:1
	s_waitcnt vmcnt(0)
	v_lshlrev_b32_e32 v32, 16, v18
	v_and_b32_e32 v33, 0xffff0000, v18
	v_add_u32_e32 v18, 0x8c10, v124
	ds_read2_b64 v[26:29], v18 offset1:1
	s_waitcnt lgkmcnt(1)
	v_pk_mul_f32 v[22:23], v[22:23], v[32:33]
	s_add_i32 s34, s34, s35
	v_cvt_pk_bf16_f32 v18, v22, v23
	v_lshlrev_b32_e32 v22, 16, v19
	v_and_b32_e32 v23, 0xffff0000, v19
	v_pk_mul_f32 v[22:23], v[24:25], v[22:23]
	s_and_b64 vcc, exec, s[30:31]
	v_cvt_pk_bf16_f32 v19, v22, v23
	v_lshlrev_b32_e32 v22, 16, v20
	v_and_b32_e32 v23, 0xffff0000, v20
	s_waitcnt lgkmcnt(0)
	v_pk_mul_f32 v[22:23], v[26:27], v[22:23]
	v_lshlrev_b32_e32 v26, 16, v14
	v_cvt_pk_bf16_f32 v20, v22, v23
	v_lshlrev_b32_e32 v22, 16, v21
	v_and_b32_e32 v23, 0xffff0000, v21
	v_pk_mul_f32 v[22:23], v[28:29], v[22:23]
	v_and_b32_e32 v27, 0xffff0000, v14
	v_cvt_pk_bf16_f32 v21, v22, v23
	global_store_dwordx4 v[30:31], v[18:21], off
	v_add_u32_e32 v14, 0x8c30, v124
	ds_read2_b64 v[22:25], v14 offset1:1
	v_add_u32_e32 v18, 0x8c20, v124
	ds_read2_b64 v[18:21], v18 offset1:1
	s_mov_b32 s33, s59
	s_waitcnt lgkmcnt(0)
	v_pk_mul_f32 v[18:19], v[18:19], v[26:27]
	s_nop 0
	v_cvt_pk_bf16_f32 v14, v18, v19
	v_lshlrev_b32_e32 v18, 16, v15
	v_and_b32_e32 v19, 0xffff0000, v15
	v_pk_mul_f32 v[18:19], v[20:21], v[18:19]
	s_nop 0
	v_cvt_pk_bf16_f32 v15, v18, v19
	v_lshlrev_b32_e32 v18, 16, v16
	v_and_b32_e32 v19, 0xffff0000, v16
	v_pk_mul_f32 v[18:19], v[22:23], v[18:19]
	s_nop 0
	v_cvt_pk_bf16_f32 v16, v18, v19
	v_lshlrev_b32_e32 v18, 16, v17
	v_and_b32_e32 v19, 0xffff0000, v17
	v_pk_mul_f32 v[18:19], v[24:25], v[18:19]
	s_nop 0
	v_cvt_pk_bf16_f32 v17, v18, v19
	global_store_dwordx4 v[30:31], v[14:17], off offset:16
	s_cbranch_vccnz .LBB0_811

; DEVI unsigned pk2(float lo, float hi) { f32x2 v = {lo, hi}; bf16x2_t b = __builtin_convertvector(v, bf16x2_t); return __builtin_bit_cast(unsigned, b); }
; DEVI float bflo(unsigned u) { return __uint_as_float(u << 16); }
; DEVI float bfhi(unsigned u) { return __uint_as_float(u & 0xffff0000u); }
; template <bool PASS_C>
; DEVI void lru_item(const P& p, int item, int next_item, uint4& u0, uint4& u1, uint4& u2, float& cpre, char* smem) {
;     ...
;     {
;         const int tok = tid >> 2, cg0 = (tid & 3) * 16;
;         uint4 r[4][2];
; #pragma unroll
;         for (int k = 0; k < 4; ++k) { r[k][0] = *(const uint4*)(us + (tok + k) * 64 + cg0); r[k][1] = *(const uint4*)(us + (tok + k) * 64 + cg0 + 8); }
;         float val[16];
; #pragma unroll
;         for (int e = 0; e < 16; ++e) {
;             const int ch = cg0 + e;
;             float a = prm[4 * 64 + ch];
; #pragma unroll
;             for (int k = 0; k < 4; ++k) {
;                 const uint4 q = r[k][e >> 3];
;                 const unsigned wd = ((e >> 1) & 3) == 0 ? q.x : (((e >> 1) & 3) == 1 ? q.y : (((e >> 1) & 3) == 2 ? q.z : q.w));
;                 a += prm[k * 64 + ch] * ((e & 1) ? bfhi(wd) : bflo(wd));
;             }
;             val[e] = a;
;         }
;         uint4 o;
;         o.x = pk2(val[0], val[1]); o.y = pk2(val[2], val[3]); o.z = pk2(val[4], val[5]); o.w = pk2(val[6], val[7]);
;         *(uint4*)(ucb + tok * 128 + ((((cg0 >> 3) + 0) ^ (tok & 7)) << 4)) = o;
;         o.x = pk2(val[8], val[9]); o.y = pk2(val[10], val[11]); o.z = pk2(val[12], val[13]); o.w = pk2(val[14], val[15]);
;         *(uint4*)(ucb + tok * 128 + ((((cg0 >> 3) + 1) ^ (tok & 7)) << 4)) = o;
;     }
.LBB0_739:
	v_lshlrev_b64 v[106:107], 10, v[22:23]
	s_waitcnt lgkmcnt(0)
	s_barrier
	ds_read_b128 v[42:45], v127 offset:35840
	ds_read_b128 v[22:25], v127 offset:35856
	ds_read_b128 v[46:49], v127 offset:35968
	ds_read_b128 v[26:29], v127 offset:35984
	ds_read_b128 v[50:53], v127 offset:36096
	ds_read_b128 v[30:33], v127 offset:36112
	ds_read_b128 v[54:57], v127 offset:36224
	ds_read_b128 v[34:37], v127 offset:36240
	ds_read_b128 v[58:61], v117 offset:33792
	ds_read_b128 v[62:65], v117 offset:32768
	ds_read_b128 v[66:69], v117 offset:32784
	ds_read_b128 v[70:73], v117 offset:32800
	ds_read_b128 v[38:41], v117 offset:32816
	ds_read_b128 v[74:77], v117 offset:33024
	ds_read_b128 v[158:161], v117 offset:33808
	s_waitcnt lgkmcnt(14)
	v_lshlrev_b32_e32 v162, 16, v42
	v_and_b32_e32 v163, 0xffff0000, v42
	s_waitcnt lgkmcnt(5)
	v_pk_fma_f32 v[58:59], v[62:63], v[162:163], v[58:59]
	ds_read_b128 v[162:165], v117 offset:33280
	ds_read_b128 v[166:169], v117 offset:33536
	ds_read_b128 v[184:187], v117 offset:33040
	v_lshlrev_b32_e32 v42, 16, v43
	v_and_b32_e32 v43, 0xffff0000, v43
	v_lshlrev_b32_e32 v170, 16, v46
	v_and_b32_e32 v171, 0xffff0000, v46
	v_lshlrev_b32_e32 v46, 16, v47
	v_and_b32_e32 v47, 0xffff0000, v47
	v_pk_fma_f32 v[42:43], v[64:65], v[42:43], v[60:61]
	v_lshlrev_b32_e32 v192, 16, v50
	v_and_b32_e32 v193, 0xffff0000, v50
	s_waitcnt lgkmcnt(4)
	v_pk_fma_f32 v[58:59], v[74:75], v[170:171], v[58:59]
	ds_read_b128 v[188:191], v117 offset:33296
	v_lshlrev_b32_e32 v50, 16, v51
	v_and_b32_e32 v51, 0xffff0000, v51
	v_pk_fma_f32 v[42:43], v[76:77], v[46:47], v[42:43]
	v_lshlrev_b32_e32 v196, 16, v54
	v_and_b32_e32 v197, 0xffff0000, v54
	s_waitcnt lgkmcnt(3)
	v_pk_fma_f32 v[58:59], v[162:163], v[192:193], v[58:59]
	ds_read_b128 v[192:195], v117 offset:33552
	v_lshlrev_b32_e32 v54, 16, v55
	v_and_b32_e32 v55, 0xffff0000, v55
	v_pk_fma_f32 v[42:43], v[164:165], v[50:51], v[42:43]
	v_lshlrev_b32_e32 v46, 16, v48
	s_waitcnt lgkmcnt(3)
	v_pk_fma_f32 v[164:165], v[168:169], v[54:55], v[42:43]
	v_lshlrev_b32_e32 v42, 16, v44
	v_and_b32_e32 v43, 0xffff0000, v44
	v_and_b32_e32 v47, 0xffff0000, v48
	v_pk_fma_f32 v[42:43], v[66:67], v[42:43], v[158:159]
	v_lshlrev_b32_e32 v50, 16, v52
	v_and_b32_e32 v51, 0xffff0000, v52
	s_waitcnt lgkmcnt(2)
	v_pk_fma_f32 v[42:43], v[184:185], v[46:47], v[42:43]
	v_lshlrev_b32_e32 v54, 16, v56
	v_and_b32_e32 v55, 0xffff0000, v56
	s_waitcnt lgkmcnt(1)
	v_pk_fma_f32 v[42:43], v[188:189], v[50:51], v[42:43]
	v_lshlrev_b32_e32 v44, 16, v49
	s_waitcnt lgkmcnt(0)
	v_pk_fma_f32 v[158:159], v[192:193], v[54:55], v[42:43]
	v_lshlrev_b32_e32 v42, 16, v45
	v_and_b32_e32 v43, 0xffff0000, v45
	v_and_b32_e32 v45, 0xffff0000, v49
	v_pk_fma_f32 v[42:43], v[68:69], v[42:43], v[160:161]
	v_lshlrev_b32_e32 v46, 16, v53
	v_and_b32_e32 v47, 0xffff0000, v53
	v_pk_fma_f32 v[42:43], v[186:187], v[44:45], v[42:43]
	v_lshlrev_b32_e32 v48, 16, v57
	v_and_b32_e32 v49, 0xffff0000, v57
	v_pk_fma_f32 v[42:43], v[190:191], v[46:47], v[42:43]
	v_lshlrev_b32_e32 v54, 16, v22
	v_pk_fma_f32 v[160:161], v[194:195], v[48:49], v[42:43]
	ds_read_b128 v[42:45], v117 offset:33824
	ds_read_b128 v[46:49], v117 offset:33056
	ds_read_b128 v[50:53], v117 offset:33840
	v_and_b32_e32 v55, 0xffff0000, v22
	v_pk_fma_f32 v[162:163], v[166:167], v[196:197], v[58:59]
	v_lshlrev_b32_e32 v22, 16, v23
	s_waitcnt lgkmcnt(2)
	v_pk_fma_f32 v[42:43], v[70:71], v[54:55], v[42:43]
	ds_read_b128 v[54:57], v117 offset:33312
	ds_read_b128 v[58:61], v117 offset:33568
	ds_read_b128 v[62:65], v117 offset:33072
	v_and_b32_e32 v23, 0xffff0000, v23
	v_lshlrev_b32_e32 v66, 16, v26
	v_and_b32_e32 v67, 0xffff0000, v26
	v_lshlrev_b32_e32 v26, 16, v27
	v_and_b32_e32 v27, 0xffff0000, v27
	v_pk_fma_f32 v[22:23], v[72:73], v[22:23], v[44:45]
	v_lshlrev_b32_e32 v74, 16, v30
	v_and_b32_e32 v75, 0xffff0000, v30
	s_waitcnt lgkmcnt(4)
	v_pk_fma_f32 v[42:43], v[46:47], v[66:67], v[42:43]
	ds_read_b128 v[66:69], v117 offset:33328
	v_lshlrev_b32_e32 v30, 16, v31
	v_and_b32_e32 v31, 0xffff0000, v31
	v_pk_fma_f32 v[22:23], v[48:49], v[26:27], v[22:23]
	v_lshlrev_b32_e32 v166, 16, v34
	v_and_b32_e32 v167, 0xffff0000, v34
	s_waitcnt lgkmcnt(3)
	v_pk_fma_f32 v[42:43], v[54:55], v[74:75], v[42:43]
	ds_read_b128 v[74:77], v117 offset:33584
	v_lshlrev_b32_e32 v34, 16, v35
	v_and_b32_e32 v35, 0xffff0000, v35
	v_pk_fma_f32 v[22:23], v[56:57], v[30:31], v[22:23]
	v_lshlrev_b32_e32 v30, 16, v28
	s_waitcnt lgkmcnt(3)
	v_pk_fma_f32 v[26:27], v[60:61], v[34:35], v[22:23]
	v_lshlrev_b32_e32 v22, 16, v24
	v_and_b32_e32 v23, 0xffff0000, v24
	v_and_b32_e32 v31, 0xffff0000, v28
	v_pk_fma_f32 v[22:23], v[38:39], v[22:23], v[50:51]
	v_lshlrev_b32_e32 v34, 16, v32
	v_and_b32_e32 v35, 0xffff0000, v32
	s_waitcnt lgkmcnt(2)
	v_pk_fma_f32 v[22:23], v[62:63], v[30:31], v[22:23]
	v_lshlrev_b32_e32 v44, 16, v36
	v_and_b32_e32 v45, 0xffff0000, v36
	s_waitcnt lgkmcnt(1)
	v_pk_fma_f32 v[22:23], v[66:67], v[34:35], v[22:23]
	v_lshlrev_b32_e32 v24, 16, v29
	s_waitcnt lgkmcnt(0)
	v_pk_fma_f32 v[30:31], v[74:75], v[44:45], v[22:23]
	v_lshlrev_b32_e32 v22, 16, v25
	v_and_b32_e32 v23, 0xffff0000, v25
	v_and_b32_e32 v25, 0xffff0000, v29
	v_pk_fma_f32 v[22:23], v[40:41], v[22:23], v[52:53]
	v_lshlrev_b32_e32 v28, 16, v33
	v_and_b32_e32 v29, 0xffff0000, v33
	v_pk_fma_f32 v[22:23], v[64:65], v[24:25], v[22:23]
	v_lshlrev_b32_e32 v32, 16, v37
	v_and_b32_e32 v33, 0xffff0000, v37
	v_pk_fma_f32 v[22:23], v[68:69], v[28:29], v[22:23]
	v_pk_fma_f32 v[42:43], v[58:59], v[166:167], v[42:43]
	v_pk_fma_f32 v[28:29], v[76:77], v[32:33], v[22:23]
	v_cvt_pk_bf16_f32 v22, v162, v163
	v_cvt_pk_bf16_f32 v23, v164, v165
	v_cvt_pk_bf16_f32 v24, v158, v159
	v_cvt_pk_bf16_f32 v25, v160, v161
	ds_write_b128 v128, v[22:25] offset:44544
	v_cvt_pk_bf16_f32 v22, v42, v43
	v_cvt_pk_bf16_f32 v23, v26, v27
	v_cvt_pk_bf16_f32 v24, v30, v31
	v_cvt_pk_bf16_f32 v25, v28, v29
	ds_write_b128 v129, v[22:25] offset:44544
	v_add_u32_e32 v22, v119, v120
	s_waitcnt lgkmcnt(0)
	s_barrier
; DEVI float bf2f(bf16_t h) { return __uint_as_float(((unsigned)h) << 16); }
; template <bool PASS_C>
; DEVI void lru_item(const P& p, int item, int next_item, uint4& u0, uint4& u1, uint4& u2, float& cpre, char* smem) {
;     ...
;     {
;         bf16x8 af[2];
; #pragma unroll
;         for (int kk = 0; kk < 2; ++kk) af[kk] = *(const bf16x8*)(ucb + (16 * w + fr) * 128 + (((kk * 4 + fq) ^ (fr & 7)) << 4));
; #pragma unroll
;         for (int n = 0; n < 16; ++n)
; #pragma unroll
;             for (int kk = 0; kk < 2; ++kk) {
;                 const bf16x8 bfr = *(const bf16x8*)(smem + (16 * n + fr) * 128 + (((kk * 4 + fq) ^ (fr & 7)) << 4));
;                 acc[n] = __builtin_amdgcn_mfma_f32_16x16x32_bf16(af[kk], bfr, acc[n], 0, 0, 0);
;             }
;     }
;     float av[4][2][4], bv[4][2][4], apre[4][2], bpre[4][2];
; #pragma unroll
;     for (int nn = 0; nn < 4; ++nn) {
;         const int ch = 16 * nn + fr;
;         float uc[4];
; #pragma unroll
;         for (int j = 0; j < 4; ++j) {
;             const int tl = 16 * w + 4 * fq + j;
;             uc[j] = bf2f(*(const bf16_t*)(ucb + tl * 128 + ((((ch >> 3)) ^ (tl & 7)) << 4) + (ch & 7) * 2));
;         }
; #pragma unroll
;         for (int d = 0; d < 2; ++d) {
;             const float ba = prm[(5 + d) * 64 + ch], bx = prm[(7 + d) * 64 + ch], nsp8 = prm[(9 + d) * 64 + ch];
; #pragma unroll
;             for (int j = 0; j < 4; ++j) {
;                 const float r = __builtin_amdgcn_rcpf(1.0f + __builtin_amdgcn_exp2f(__builtin_fmaf(acc[(2 * d) * 4 + nn][j], -LOG2E, ba)));
;                 const float ig = __builtin_amdgcn_rcpf(1.0f + __builtin_amdgcn_exp2f(__builtin_fmaf(acc[(2 * d + 1) * 4 + nn][j], -LOG2E, bx)));
;                 const float a_ = __builtin_amdgcn_exp2f(nsp8 * r);
;                 av[nn][d][j] = a_;
;                 bv[nn][d][j] = __builtin_amdgcn_sqrtf(__builtin_fmaf(-a_, a_, 1.0f)) * ig * uc[j];
	ds_read_b128 v[26:29], v22 offset:44544
	v_add_u32_e32 v87, v118, v120
	ds_read_b128 v[22:25], v87
	v_add_u32_e32 v30, v119, v121
	v_add_u32_e32 v89, v118, v121
	ds_read_b128 v[158:161], v30 offset:44544
	ds_read_b32 v93, v122 offset:35072
	s_waitcnt lgkmcnt(2)
	v_mfma_f32_16x16x32_bf16 v[22:25], v[26:29], v[22:25], 0
	ds_read_b128 v[30:33], v89
	ds_read_b128 v[162:165], v87 offset:30720
	s_waitcnt lgkmcnt(1)
	v_mfma_f32_16x16x32_bf16 v[166:169], v[158:161], v[30:33], v[22:25]
	s_nop 3
	ds_read_b128 v[22:25], v87 offset:2048
	ds_read_b128 v[30:33], v87 offset:4096
	ds_read_b128 v[34:37], v89 offset:2048
	ds_read_b128 v[38:41], v89 offset:4096
	s_waitcnt lgkmcnt(3)
	v_mfma_f32_16x16x32_bf16 v[22:25], v[26:29], v[22:25], 0
	s_waitcnt lgkmcnt(1)
	v_mfma_f32_16x16x32_bf16 v[62:65], v[158:161], v[34:37], v[22:25]
	v_mfma_f32_16x16x32_bf16 v[22:25], v[26:29], v[30:33], 0
	s_waitcnt lgkmcnt(0)
	v_mfma_f32_16x16x32_bf16 v[46:49], v[158:161], v[38:41], v[22:25]
	s_nop 5
	ds_read_b128 v[22:25], v87 offset:6144
	ds_read_b128 v[34:37], v87 offset:8192
	ds_read_b128 v[30:33], v89 offset:6144
	ds_read_b128 v[38:41], v89 offset:8192
	s_waitcnt lgkmcnt(3)
	v_mfma_f32_16x16x32_bf16 v[22:25], v[26:29], v[22:25], 0
	s_waitcnt lgkmcnt(1)
	v_mfma_f32_16x16x32_bf16 v[30:33], v[158:161], v[30:33], v[22:25]
	v_mfma_f32_16x16x32_bf16 v[22:25], v[26:29], v[34:37], 0
	s_waitcnt lgkmcnt(0)
	v_mfma_f32_16x16x32_bf16 v[184:187], v[158:161], v[38:41], v[22:25]
	s_nop 5
	ds_read_b128 v[22:25], v87 offset:10240
	ds_read_b128 v[34:37], v87 offset:12288
	ds_read_b128 v[38:41], v89 offset:10240
	ds_read_b128 v[42:45], v89 offset:12288
	s_waitcnt lgkmcnt(3)
	v_mfma_f32_16x16x32_bf16 v[22:25], v[26:29], v[22:25], 0
	s_waitcnt lgkmcnt(1)
	v_mfma_f32_16x16x32_bf16 v[66:69], v[158:161], v[38:41], v[22:25]
	v_mfma_f32_16x16x32_bf16 v[22:25], v[26:29], v[34:37], 0
	s_waitcnt lgkmcnt(0)
	v_mfma_f32_16x16x32_bf16 v[50:53], v[158:161], v[42:45], v[22:25]
	s_nop 5
	ds_read_b128 v[22:25], v87 offset:14336
	ds_read_b128 v[38:41], v87 offset:16384
	ds_read_b128 v[34:37], v89 offset:14336
	ds_read_b128 v[42:45], v89 offset:16384
	s_waitcnt lgkmcnt(3)
	v_mfma_f32_16x16x32_bf16 v[22:25], v[26:29], v[22:25], 0
	s_waitcnt lgkmcnt(1)
	v_mfma_f32_16x16x32_bf16 v[34:37], v[158:161], v[34:37], v[22:25]
	v_mfma_f32_16x16x32_bf16 v[22:25], v[26:29], v[38:41], 0
	s_waitcnt lgkmcnt(0)
	v_mfma_f32_16x16x32_bf16 v[70:73], v[158:161], v[42:45], v[22:25]
	s_nop 5
	ds_read_b128 v[22:25], v87 offset:18432
	ds_read_b128 v[38:41], v87 offset:20480
	ds_read_b128 v[42:45], v89 offset:18432
	ds_read_b128 v[58:61], v89 offset:20480
	s_waitcnt lgkmcnt(3)
	v_mfma_f32_16x16x32_bf16 v[22:25], v[26:29], v[22:25], 0
	s_waitcnt lgkmcnt(1)
	v_mfma_f32_16x16x32_bf16 v[54:57], v[158:161], v[42:45], v[22:25]
	v_mfma_f32_16x16x32_bf16 v[22:25], v[26:29], v[38:41], 0
	s_waitcnt lgkmcnt(0)
	v_mfma_f32_16x16x32_bf16 v[38:41], v[158:161], v[58:61], v[22:25]
	s_nop 5
	ds_read_b128 v[22:25], v87 offset:22528
	ds_read_b128 v[42:45], v87 offset:24576
	ds_read_b128 v[58:61], v89 offset:22528
	ds_read_b128 v[74:77], v89 offset:24576
	s_waitcnt lgkmcnt(2)
	v_mfma_f32_16x16x32_bf16 v[42:45], v[26:29], v[42:45], 0
	v_mfma_f32_16x16x32_bf16 v[22:25], v[26:29], v[22:25], 0
	s_waitcnt lgkmcnt(0)
	v_mfma_f32_16x16x32_bf16 v[74:77], v[158:161], v[74:77], v[42:45]
	s_nop 4
	ds_read_b128 v[42:45], v87 offset:26624
	ds_read_b128 v[188:191], v87 offset:28672
	v_mfma_f32_16x16x32_bf16 v[22:25], v[158:161], v[58:61], v[22:25]
	ds_read_b128 v[58:61], v89 offset:26624
	ds_read_b128 v[192:195], v89 offset:28672
	s_waitcnt lgkmcnt(3)
	v_mfma_f32_16x16x32_bf16 v[42:45], v[26:29], v[42:45], 0
	s_waitcnt lgkmcnt(1)
	v_mfma_f32_16x16x32_bf16 v[58:61], v[158:161], v[58:61], v[42:45]
	v_mfma_f32_16x16x32_bf16 v[42:45], v[26:29], v[188:191], 0
	v_mfma_f32_16x16x32_bf16 v[26:29], v[26:29], v[162:165], 0
	ds_read2st64_b32 v[170:171], v122 offset0:133 offset1:135
	ds_read_b128 v[162:165], v89 offset:30720
	ds_read_u16 v87, v130 offset:44544
	ds_read_u16 v89, v131 offset:44544
	ds_read_u16 v91, v132 offset:44544
	s_waitcnt lgkmcnt(4)
	v_fmamk_f32 v95, v166, 0xbfb8aa3b, v170
	v_exp_f32_e32 v95, v95
	v_mfma_f32_16x16x32_bf16 v[42:45], v[158:161], v[192:195], v[42:45]
	v_fmamk_f32 v99, v168, 0xbfb8aa3b, v170
	v_fmamk_f32 v101, v186, 0xbfb8aa3b, v171
	v_exp_f32_e32 v99, v99
	s_waitcnt lgkmcnt(3)
	v_mfma_f32_16x16x32_bf16 v[26:29], v[158:161], v[162:165], v[26:29]
	s_waitcnt lgkmcnt(2)
	v_lshlrev_b32_e32 v164, 16, v87
	s_waitcnt lgkmcnt(1)
	v_lshlrev_b32_e32 v161, 16, v89
	v_add_f32_e32 v87, 1.0, v95
	v_fmamk_f32 v89, v184, 0xbfb8aa3b, v171
	v_exp_f32_e32 v89, v89
	v_rcp_f32_e32 v87, v87
	s_waitcnt lgkmcnt(0)
	v_lshlrev_b32_e32 v162, 16, v91
	ds_read_u16 v91, v133 offset:44544
	v_add_f32_e32 v95, 1.0, v89
	v_mul_f32_e32 v87, v93, v87
	v_exp_f32_e32 v89, v87
	v_rcp_f32_e32 v87, v95
	v_fmamk_f32 v95, v167, 0xbfb8aa3b, v170
	v_exp_f32_e32 v95, v95
	s_waitcnt lgkmcnt(0)
; template <bool PASS_C>
; DEVI void lru_item(const P& p, int item, int next_item, uint4& u0, uint4& u1, uint4& u2, float& cpre, char* smem) {
;     ...
;     float av[4][2][4], bv[4][2][4], apre[4][2], bpre[4][2];
; #pragma unroll
;     for (int nn = 0; nn < 4; ++nn) {
;         const int ch = 16 * nn + fr;
;         float uc[4];
; #pragma unroll
;         for (int j = 0; j < 4; ++j) {
;             const int tl = 16 * w + 4 * fq + j;
;             uc[j] = bf2f(*(const bf16_t*)(ucb + tl * 128 + ((((ch >> 3)) ^ (tl & 7)) << 4) + (ch & 7) * 2));
;         }
; #pragma unroll
;         for (int d = 0; d < 2; ++d) {
;             const float ba = prm[(5 + d) * 64 + ch], bx = prm[(7 + d) * 64 + ch], nsp8 = prm[(9 + d) * 64 + ch];
; #pragma unroll
;             for (int j = 0; j < 4; ++j) {
;                 const float r = __builtin_amdgcn_rcpf(1.0f + __builtin_amdgcn_exp2f(__builtin_fmaf(acc[(2 * d) * 4 + nn][j], -LOG2E, ba)));
;                 const float ig = __builtin_amdgcn_rcpf(1.0f + __builtin_amdgcn_exp2f(__builtin_fmaf(acc[(2 * d + 1) * 4 + nn][j], -LOG2E, bx)));
;                 const float a_ = __builtin_amdgcn_exp2f(nsp8 * r);
;                 av[nn][d][j] = a_;
;                 bv[nn][d][j] = __builtin_amdgcn_sqrtf(__builtin_fmaf(-a_, a_, 1.0f)) * ig * uc[j];
;             }
;             float A = 1.f, Bq = 0.f;
;             if (d == 0) {
; #pragma unroll
;                 for (int j = 0; j < 4; ++j) { Bq = av[nn][d][j] * Bq + bv[nn][d][j]; A *= av[nn][d][j]; }
;             } else {
; #pragma unroll
;                 for (int j = 3; j >= 0; --j) { Bq = av[nn][d][j] * Bq + bv[nn][d][j]; A *= av[nn][d][j]; }
;             }
;             float Ag[4], Bg[4];
;             rowgather4(A, Ag); rowgather4(Bq, Bg);
;             float AW = 1.f, BW = 0.f, AP = 1.f, BP = 0.f;
;             if (d == 0) {
; #pragma unroll
;                 for (int g = 0; g < 4; ++g) {
;                     if (g == fq) { AP = AW; BP = BW; }
;                     BW = Ag[g] * BW + Bg[g]; AW *= Ag[g];
;                 }
;             } else {
; #pragma unroll
;                 for (int g = 3; g >= 0; --g) {
;                     if (g == fq) { AP = AW; BP = BW; }
;                     BW = Ag[g] * BW + Bg[g]; AW *= Ag[g];
;                 }
;             }
;             apre[nn][d] = AP; bpre[nn][d] = BP;
	v_lshlrev_b32_e32 v163, 16, v91
	v_fma_f32 v97, -v89, v89, 1.0
	v_sqrt_f32_e32 v97, v97
	v_add_f32_e32 v91, 1.0, v95
	v_rcp_f32_e32 v91, v91
	v_fmamk_f32 v95, v185, 0xbfb8aa3b, v171
	v_exp_f32_e32 v95, v95
	v_mul_f32_e32 v87, v87, v97
	v_mul_f32_e32 v91, v93, v91
	v_exp_f32_e32 v91, v91
	v_add_f32_e32 v95, 1.0, v95
	v_rcp_f32_e32 v95, v95
	v_exp_f32_e32 v101, v101
	v_fma_f32 v97, -v91, v91, 1.0
	v_sqrt_f32_e32 v97, v97
	v_fmac_f32_e32 v171, 0xbfb8aa3b, v187
	v_exp_f32_e32 v105, v171
	v_mul_f32_e32 v87, v87, v164
	v_mul_f32_e32 v97, v95, v97
	v_add_f32_e32 v95, 1.0, v99
	v_add_f32_e32 v99, 1.0, v101
	v_fmamk_f32 v101, v169, 0xbfb8aa3b, v170
	v_exp_f32_e32 v101, v101
	v_rcp_f32_e32 v95, v95
	v_rcp_f32_e32 v99, v99
	v_add_f32_e32 v101, 1.0, v101
	v_rcp_f32_e32 v101, v101
	v_mul_f32_e32 v95, v93, v95
	v_exp_f32_e32 v95, v95
	v_mul_f32_e32 v93, v93, v101
	v_exp_f32_e32 v101, v93
	v_add_f32_e32 v93, 1.0, v105
	v_fma_f32 v103, -v95, v95, 1.0
	v_rcp_f32_e32 v105, v93
	v_fma_f32 v93, -v101, v101, 1.0
	v_sqrt_f32_e32 v103, v103
	v_sqrt_f32_e32 v157, v93
	v_mul_f32_e32 v93, v97, v161
	v_mul_f32_e32 v97, v99, v103
	v_mul_f32_e32 v99, v105, v157
	v_fma_f32 v105, 0, v89, v87
	v_mul_f32_e32 v97, v97, v162
	v_mul_f32_e32 v103, v89, v91
	v_fma_f32 v105, v91, v105, v93
	v_mul_f32_e32 v99, v99, v163
	v_mul_f32_e32 v103, v95, v103
	v_fma_f32 v105, v95, v105, v97
	v_mul_f32_e32 v103, v101, v103
	v_fma_f32 v105, v101, v105, v99
	v_mov_b32_e32 v159, v103
	v_mov_b32_e32 v157, v105
	s_nop 0
	v_permlane16_swap_b32_e32 v103, v159
	v_permlane16_swap_b32_e32 v105, v157
	v_mov_b32_e32 v160, v103
	v_mov_b32_e32 v158, v105
	s_nop 0
	v_permlane32_swap_b32_e32 v103, v160
	v_mov_b32_e32 v165, v159
	v_permlane32_swap_b32_e32 v105, v158
	v_mov_b32_e32 v166, v157
	v_permlane32_swap_b32_e32 v159, v165
	s_nop 0
	v_permlane32_swap_b32_e32 v157, v166
	v_fmac_f32_e32 v105, 0, v103
	v_fmac_f32_e32 v157, v105, v159
	v_mul_f32_e32 v159, v103, v159
	v_fmac_f32_e32 v158, v157, v160
	v_mul_f32_e32 v160, v159, v160
	s_and_saveexec_b64 s[28:29], s[10:11]
	v_mul_f32_e32 v167, v158, v165
	v_mul_f32_e32 v168, v160, v165
	v_add_f32_e32 v169, v167, v166
	ds_write_b64 v149, v[168:169] offset:52736
	s_or_b64 exec, exec, s[28:29]
	ds_read2st64_b32 v[166:167], v122 offset0:134 offset1:136
	ds_read_b32 v165, v122 offset:35328
	s_waitcnt lgkmcnt(1)
	v_fmamk_f32 v70, v70, 0xbfb8aa3b, v166
	v_exp_f32_e32 v70, v70
	v_fmamk_f32 v71, v71, 0xbfb8aa3b, v166
	v_exp_f32_e32 v71, v71
	v_fmamk_f32 v74, v74, 0xbfb8aa3b, v167
	v_add_f32_e32 v70, 1.0, v70
	v_rcp_f32_e32 v70, v70
	v_add_f32_e32 v71, 1.0, v71
	v_exp_f32_e32 v74, v74
	v_rcp_f32_e32 v71, v71
	s_waitcnt lgkmcnt(0)
	v_mul_f32_e32 v70, v165, v70
	v_exp_f32_e32 v70, v70
	v_fmamk_f32 v75, v75, 0xbfb8aa3b, v167
	v_add_f32_e32 v74, 1.0, v74
	v_mul_f32_e32 v71, v165, v71
	v_fma_f32 v168, -v70, v70, 1.0
	v_fmamk_f32 v72, v72, 0xbfb8aa3b, v166
	v_fmamk_f32 v73, v73, 0xbfb8aa3b, v166
	v_exp_f32_e32 v75, v75
	v_rcp_f32_e32 v74, v74
	v_exp_f32_e32 v71, v71
	v_sqrt_f32_e32 v168, v168
	v_exp_f32_e32 v72, v72
	v_exp_f32_e32 v73, v73
	v_add_f32_e32 v75, 1.0, v75
	v_fma_f32 v169, -v71, v71, 1.0
	v_mul_f32_e32 v74, v74, v168
	v_fmamk_f32 v76, v76, 0xbfb8aa3b, v167
	v_add_f32_e32 v72, 1.0, v72
	v_add_f32_e32 v73, 1.0, v73
	v_rcp_f32_e32 v75, v75
	v_mul_f32_e32 v74, v74, v164
	v_sqrt_f32_e32 v164, v169
	v_exp_f32_e32 v76, v76
	v_rcp_f32_e32 v72, v72
	v_rcp_f32_e32 v73, v73
	v_fmac_f32_e32 v167, 0xbfb8aa3b, v77
	v_mul_f32_e32 v164, v75, v164
	v_add_f32_e32 v75, 1.0, v76
	v_mul_f32_e32 v72, v165, v72
	v_exp_f32_e32 v77, v167
	v_mul_f32_e32 v73, v165, v73
	v_exp_f32_e32 v72, v72
	v_rcp_f32_e32 v76, v75
	v_exp_f32_e32 v75, v73
	v_add_f32_e32 v73, 1.0, v77
	v_fma_f32 v166, -v72, v72, 1.0
	v_rcp_f32_e32 v77, v73
	v_fma_f32 v73, -v75, v75, 1.0
	v_sqrt_f32_e32 v165, v166
	v_sqrt_f32_e32 v166, v73
	v_mul_f32_e32 v73, v164, v161
	v_mul_f32_e32 v161, v75, v72
	v_mul_f32_e32 v76, v76, v165
	v_mul_f32_e32 v77, v77, v166
	v_mul_f32_e32 v77, v77, v163
	v_mul_f32_e32 v161, v71, v161
	v_mul_f32_e32 v76, v76, v162
	v_mul_f32_e32 v165, v70, v161
	v_fma_f32 v161, 0, v75, v77
	v_fma_f32 v161, v72, v161, v76
	v_fma_f32 v161, v71, v161, v73
	v_fma_f32 v168, v70, v161, v74
	v_mov_b32_e32 v167, v165
	v_mov_b32_e32 v161, v168
	s_nop 0
	v_permlane16_swap_b32_e32 v165, v167
	v_permlane16_swap_b32_e32 v168, v161
	v_mov_b32_e32 v162, v167
	v_mov_b32_e32 v164, v161
	v_mov_b32_e32 v166, v165
	v_permlane32_swap_b32_e32 v167, v162
	v_mov_b32_e32 v163, v168
	v_permlane32_swap_b32_e32 v161, v164
	v_permlane32_swap_b32_e32 v165, v166
	v_permlane32_swap_b32_e32 v168, v163
	v_fmac_f32_e32 v164, 0, v162
	v_fmac_f32_e32 v163, v164, v166
	v_mul_f32_e32 v166, v166, v162
	v_fmac_f32_e32 v161, v163, v167
	v_mul_f32_e32 v167, v166, v167
	s_and_saveexec_b64 s[28:29], s[10:11]
	v_mul_f32_e32 v169, v161, v165
	v_mul_f32_e32 v170, v167, v165
	v_add_f32_e32 v171, v169, v168
	ds_write_b64 v149, v[170:171] offset:53248
	s_or_b64 exec, exec, s[28:29]
	v_add_u32_e32 v186, 64, v122
	ds_read2st64_b32 v[168:169], v186 offset0:133 offset1:135
	ds_read_u16 v165, v134 offset:44544
	ds_read_u16 v170, v135 offset:44544
	ds_read_u16 v171, v136 offset:44544
	ds_read_u16 v173, v137 offset:44544
	ds_read_b32 v187, v122 offset:35136
	s_waitcnt lgkmcnt(4)
	v_lshlrev_b32_e32 v185, 16, v165
	s_waitcnt lgkmcnt(3)
	v_lshlrev_b32_e32 v183, 16, v170
	s_waitcnt lgkmcnt(2)
	v_lshlrev_b32_e32 v177, 16, v171
	v_fmamk_f32 v62, v62, 0xbfb8aa3b, v168
	v_exp_f32_e32 v62, v62
	v_fmamk_f32 v63, v63, 0xbfb8aa3b, v168
	v_fmamk_f32 v66, v66, 0xbfb8aa3b, v169
	v_exp_f32_e32 v63, v63
	v_add_f32_e32 v62, 1.0, v62
	v_rcp_f32_e32 v62, v62
	v_exp_f32_e32 v66, v66
	v_add_f32_e32 v63, 1.0, v63
	v_rcp_f32_e32 v63, v63
	s_waitcnt lgkmcnt(0)
; template <bool PASS_C>
; DEVI void lru_item(const P& p, int item, int next_item, uint4& u0, uint4& u1, uint4& u2, float& cpre, char* smem) {
;     ...
;     float av[4][2][4], bv[4][2][4], apre[4][2], bpre[4][2];
; #pragma unroll
;     for (int nn = 0; nn < 4; ++nn) {
;         const int ch = 16 * nn + fr;
;         float uc[4];
; #pragma unroll
;         for (int j = 0; j < 4; ++j) {
;             const int tl = 16 * w + 4 * fq + j;
;             uc[j] = bf2f(*(const bf16_t*)(ucb + tl * 128 + ((((ch >> 3)) ^ (tl & 7)) << 4) + (ch & 7) * 2));
;         }
; #pragma unroll
;         for (int d = 0; d < 2; ++d) {
;             const float ba = prm[(5 + d) * 64 + ch], bx = prm[(7 + d) * 64 + ch], nsp8 = prm[(9 + d) * 64 + ch];
; #pragma unroll
;             for (int j = 0; j < 4; ++j) {
;                 const float r = __builtin_amdgcn_rcpf(1.0f + __builtin_amdgcn_exp2f(__builtin_fmaf(acc[(2 * d) * 4 + nn][j], -LOG2E, ba)));
;                 const float ig = __builtin_amdgcn_rcpf(1.0f + __builtin_amdgcn_exp2f(__builtin_fmaf(acc[(2 * d + 1) * 4 + nn][j], -LOG2E, bx)));
;                 const float a_ = __builtin_amdgcn_exp2f(nsp8 * r);
;                 av[nn][d][j] = a_;
;                 bv[nn][d][j] = __builtin_amdgcn_sqrtf(__builtin_fmaf(-a_, a_, 1.0f)) * ig * uc[j];
;             }
;             float A = 1.f, Bq = 0.f;
;             if (d == 0) {
; #pragma unroll
;                 for (int j = 0; j < 4; ++j) { Bq = av[nn][d][j] * Bq + bv[nn][d][j]; A *= av[nn][d][j]; }
;             } else {
; #pragma unroll
;                 for (int j = 3; j >= 0; --j) { Bq = av[nn][d][j] * Bq + bv[nn][d][j]; A *= av[nn][d][j]; }
;             }
;             float Ag[4], Bg[4];
;             rowgather4(A, Ag); rowgather4(Bq, Bg);
;             float AW = 1.f, BW = 0.f, AP = 1.f, BP = 0.f;
;             if (d == 0) {
; #pragma unroll
;                 for (int g = 0; g < 4; ++g) {
;                     if (g == fq) { AP = AW; BP = BW; }
;                     BW = Ag[g] * BW + Bg[g]; AW *= Ag[g];
;                 }
;             } else {
; #pragma unroll
;                 for (int g = 3; g >= 0; --g) {
;                     if (g == fq) { AP = AW; BP = BW; }
;                     BW = Ag[g] * BW + Bg[g]; AW *= Ag[g];
;                 }
;             }
;             apre[nn][d] = AP; bpre[nn][d] = BP;
	v_mul_f32_e32 v62, v187, v62
	v_add_f32_e32 v165, 1.0, v66
	v_exp_f32_e32 v66, v62
	v_rcp_f32_e32 v62, v165
	v_fmamk_f32 v67, v67, 0xbfb8aa3b, v169
	v_mul_f32_e32 v63, v187, v63
	v_fma_f32 v165, -v66, v66, 1.0
	v_sqrt_f32_e32 v165, v165
	v_exp_f32_e32 v67, v67
	v_exp_f32_e32 v63, v63
	v_fmamk_f32 v64, v64, 0xbfb8aa3b, v168
	v_exp_f32_e32 v64, v64
	v_mul_f32_e32 v62, v62, v165
	v_add_f32_e32 v67, 1.0, v67
	v_fma_f32 v165, -v63, v63, 1.0
	v_rcp_f32_e32 v67, v67
	v_sqrt_f32_e32 v165, v165
	v_add_f32_e32 v64, 1.0, v64
	v_rcp_f32_e32 v64, v64
	v_fmamk_f32 v65, v65, 0xbfb8aa3b, v168
	v_mul_f32_e32 v67, v67, v165
	v_exp_f32_e32 v165, v65
	v_mul_f32_e32 v64, v187, v64
	v_exp_f32_e32 v65, v64
	v_fmamk_f32 v68, v68, 0xbfb8aa3b, v169
	v_add_f32_e32 v64, 1.0, v165
	v_rcp_f32_e32 v64, v64
	v_fmac_f32_e32 v169, 0xbfb8aa3b, v69
	v_exp_f32_e32 v168, v169
	v_exp_f32_e32 v68, v68
	v_mul_f32_e32 v64, v187, v64
	v_exp_f32_e32 v69, v64
	v_add_f32_e32 v64, 1.0, v168
	v_add_f32_e32 v68, 1.0, v68
	v_fma_f32 v165, -v65, v65, 1.0
	v_rcp_f32_e32 v168, v64
	v_fma_f32 v64, -v69, v69, 1.0
	v_rcp_f32_e32 v68, v68
	v_sqrt_f32_e32 v165, v165
	v_sqrt_f32_e32 v169, v64
	v_mul_f32_e32 v62, v62, v185
	v_mul_f32_e32 v64, v67, v183
	v_mul_f32_e32 v67, v68, v165
	v_mul_f32_e32 v68, v168, v169
	v_fma_f32 v168, 0, v66, v62
	v_lshlrev_b32_e32 v184, 16, v173
	v_mul_f32_e32 v67, v67, v177
	v_mul_f32_e32 v165, v66, v63
	v_fma_f32 v168, v63, v168, v64
	v_mul_f32_e32 v68, v68, v184
	v_mul_f32_e32 v165, v65, v165
	v_fma_f32 v168, v65, v168, v67
	v_mul_f32_e32 v165, v69, v165
	v_fma_f32 v168, v69, v168, v68
	v_mov_b32_e32 v171, v165
	v_mov_b32_e32 v169, v168
	s_nop 0
	v_permlane16_swap_b32_e32 v165, v171
	v_permlane16_swap_b32_e32 v168, v169
	v_mov_b32_e32 v173, v165
	v_mov_b32_e32 v170, v168
	s_nop 0
	v_permlane32_swap_b32_e32 v165, v173
	v_mov_b32_e32 v187, v171
	v_permlane32_swap_b32_e32 v168, v170
	v_mov_b32_e32 v188, v169
	v_permlane32_swap_b32_e32 v171, v187
	s_nop 0
	v_permlane32_swap_b32_e32 v169, v188
	v_fmac_f32_e32 v168, 0, v165
	v_fmac_f32_e32 v169, v168, v171
	v_mul_f32_e32 v171, v165, v171
	v_fmac_f32_e32 v170, v169, v173
	v_mul_f32_e32 v173, v171, v173
	s_and_saveexec_b64 s[28:29], s[10:11]
	v_mul_f32_e32 v189, v170, v187
	v_mul_f32_e32 v190, v173, v187
	v_add_f32_e32 v191, v189, v188
	ds_write_b64 v150, v[190:191] offset:52736
	s_or_b64 exec, exec, s[28:29]
	ds_read2st64_b32 v[186:187], v186 offset0:134 offset1:136
	ds_read_b32 v188, v122 offset:35392
	s_waitcnt lgkmcnt(1)
	v_fmamk_f32 v54, v54, 0xbfb8aa3b, v186
	v_exp_f32_e32 v54, v54
	v_fmamk_f32 v55, v55, 0xbfb8aa3b, v186
	v_exp_f32_e32 v55, v55
	v_fmamk_f32 v58, v58, 0xbfb8aa3b, v187
	v_add_f32_e32 v54, 1.0, v54
	v_rcp_f32_e32 v54, v54
	v_add_f32_e32 v55, 1.0, v55
	v_exp_f32_e32 v58, v58
	v_rcp_f32_e32 v55, v55
	s_waitcnt lgkmcnt(0)
	v_mul_f32_e32 v54, v188, v54
	v_exp_f32_e32 v54, v54
	v_fmamk_f32 v56, v56, 0xbfb8aa3b, v186
	v_fmamk_f32 v59, v59, 0xbfb8aa3b, v187
	v_add_f32_e32 v58, 1.0, v58
	v_mul_f32_e32 v55, v188, v55
	v_fma_f32 v189, -v54, v54, 1.0
	v_exp_f32_e32 v56, v56
	v_fmamk_f32 v57, v57, 0xbfb8aa3b, v186
	v_exp_f32_e32 v59, v59
	v_rcp_f32_e32 v58, v58
	v_exp_f32_e32 v55, v55
	v_sqrt_f32_e32 v189, v189
	v_exp_f32_e32 v57, v57
	v_add_f32_e32 v56, 1.0, v56
	v_add_f32_e32 v59, 1.0, v59
	v_fma_f32 v190, -v55, v55, 1.0
	v_mul_f32_e32 v58, v58, v189
	v_fmamk_f32 v60, v60, 0xbfb8aa3b, v187
	v_rcp_f32_e32 v56, v56
	v_add_f32_e32 v57, 1.0, v57
	v_rcp_f32_e32 v59, v59
	v_mul_f32_e32 v58, v58, v185
	v_sqrt_f32_e32 v185, v190
	v_exp_f32_e32 v60, v60
	v_rcp_f32_e32 v57, v57
	v_mul_f32_e32 v56, v188, v56
	v_fmac_f32_e32 v187, 0xbfb8aa3b, v61
	v_mul_f32_e32 v185, v59, v185
	v_add_f32_e32 v59, 1.0, v60
	v_exp_f32_e32 v56, v56
	v_exp_f32_e32 v61, v187
	v_mul_f32_e32 v57, v188, v57
	v_rcp_f32_e32 v60, v59
	v_exp_f32_e32 v59, v57
	v_fma_f32 v186, -v56, v56, 1.0
	v_add_f32_e32 v57, 1.0, v61
	v_sqrt_f32_e32 v186, v186
	v_rcp_f32_e32 v61, v57
	v_fma_f32 v57, -v59, v59, 1.0
	v_sqrt_f32_e32 v187, v57
	v_mul_f32_e32 v60, v60, v186
	v_mul_f32_e32 v60, v60, v177
	v_mul_f32_e32 v177, v59, v56
	v_mul_f32_e32 v61, v61, v187
	v_mul_f32_e32 v61, v61, v184
	v_mul_f32_e32 v177, v55, v177
	v_mul_f32_e32 v186, v54, v177
	v_fma_f32 v177, 0, v59, v61
	v_mul_f32_e32 v57, v185, v183
	v_fma_f32 v177, v56, v177, v60
	v_fma_f32 v177, v55, v177, v57
	v_fma_f32 v189, v54, v177, v58
	v_mov_b32_e32 v188, v186
	v_mov_b32_e32 v177, v189
	s_nop 0
	v_permlane16_swap_b32_e32 v186, v188
	v_permlane16_swap_b32_e32 v189, v177
	v_mov_b32_e32 v183, v188
	v_mov_b32_e32 v185, v177
	v_mov_b32_e32 v187, v186
	v_permlane32_swap_b32_e32 v188, v183
	v_mov_b32_e32 v184, v189
	v_permlane32_swap_b32_e32 v177, v185
	v_permlane32_swap_b32_e32 v186, v187
	v_permlane32_swap_b32_e32 v189, v184
	v_fmac_f32_e32 v185, 0, v183
	v_fmac_f32_e32 v184, v185, v187
	v_mul_f32_e32 v187, v187, v183
	v_fmac_f32_e32 v177, v184, v188
	v_mul_f32_e32 v188, v187, v188
	s_and_saveexec_b64 s[28:29], s[10:11]
	v_mul_f32_e32 v191, v177, v186
	v_mul_f32_e32 v190, v188, v186
	v_add_f32_e32 v191, v191, v189
	ds_write_b64 v150, v[190:191] offset:53248
	s_or_b64 exec, exec, s[28:29]
	v_add_u32_e32 v198, 0x80, v122
	ds_read2st64_b32 v[190:191], v198 offset0:133 offset1:135
	ds_read_u16 v186, v138 offset:44544
	ds_read_u16 v189, v139 offset:44544
	ds_read_u16 v192, v140 offset:44544
	ds_read_u16 v193, v141 offset:44544
	ds_read_b32 v199, v122 offset:35200
	s_waitcnt lgkmcnt(4)
	v_lshlrev_b32_e32 v197, 16, v186
	s_waitcnt lgkmcnt(3)
	v_lshlrev_b32_e32 v195, 16, v189
	s_waitcnt lgkmcnt(2)
; template <bool PASS_C>
; DEVI void lru_item(const P& p, int item, int next_item, uint4& u0, uint4& u1, uint4& u2, float& cpre, char* smem) {
;     ...
;     float av[4][2][4], bv[4][2][4], apre[4][2], bpre[4][2];
; #pragma unroll
;     for (int nn = 0; nn < 4; ++nn) {
;         const int ch = 16 * nn + fr;
;         float uc[4];
; #pragma unroll
;         for (int j = 0; j < 4; ++j) {
;             const int tl = 16 * w + 4 * fq + j;
;             uc[j] = bf2f(*(const bf16_t*)(ucb + tl * 128 + ((((ch >> 3)) ^ (tl & 7)) << 4) + (ch & 7) * 2));
;         }
; #pragma unroll
;         for (int d = 0; d < 2; ++d) {
;             const float ba = prm[(5 + d) * 64 + ch], bx = prm[(7 + d) * 64 + ch], nsp8 = prm[(9 + d) * 64 + ch];
; #pragma unroll
;             for (int j = 0; j < 4; ++j) {
;                 const float r = __builtin_amdgcn_rcpf(1.0f + __builtin_amdgcn_exp2f(__builtin_fmaf(acc[(2 * d) * 4 + nn][j], -LOG2E, ba)));
;                 const float ig = __builtin_amdgcn_rcpf(1.0f + __builtin_amdgcn_exp2f(__builtin_fmaf(acc[(2 * d + 1) * 4 + nn][j], -LOG2E, bx)));
;                 const float a_ = __builtin_amdgcn_exp2f(nsp8 * r);
;                 av[nn][d][j] = a_;
;                 bv[nn][d][j] = __builtin_amdgcn_sqrtf(__builtin_fmaf(-a_, a_, 1.0f)) * ig * uc[j];
;             }
;             float A = 1.f, Bq = 0.f;
;             if (d == 0) {
; #pragma unroll
;                 for (int j = 0; j < 4; ++j) { Bq = av[nn][d][j] * Bq + bv[nn][d][j]; A *= av[nn][d][j]; }
;             } else {
; #pragma unroll
;                 for (int j = 3; j >= 0; --j) { Bq = av[nn][d][j] * Bq + bv[nn][d][j]; A *= av[nn][d][j]; }
;             }
;             float Ag[4], Bg[4];
;             rowgather4(A, Ag); rowgather4(Bq, Bg);
;             float AW = 1.f, BW = 0.f, AP = 1.f, BP = 0.f;
;             if (d == 0) {
; #pragma unroll
;                 for (int g = 0; g < 4; ++g) {
;                     if (g == fq) { AP = AW; BP = BW; }
;                     BW = Ag[g] * BW + Bg[g]; AW *= Ag[g];
;                 }
;             } else {
; #pragma unroll
;                 for (int g = 3; g >= 0; --g) {
;                     if (g == fq) { AP = AW; BP = BW; }
;                     BW = Ag[g] * BW + Bg[g]; AW *= Ag[g];
;                 }
;             }
;             apre[nn][d] = AP; bpre[nn][d] = BP;
	v_lshlrev_b32_e32 v194, 16, v192
	v_fmamk_f32 v46, v46, 0xbfb8aa3b, v190
	v_exp_f32_e32 v46, v46
	v_fmamk_f32 v47, v47, 0xbfb8aa3b, v190
	v_fmamk_f32 v50, v50, 0xbfb8aa3b, v191
	v_exp_f32_e32 v47, v47
	v_add_f32_e32 v46, 1.0, v46
	v_rcp_f32_e32 v46, v46
	v_exp_f32_e32 v50, v50
	v_add_f32_e32 v47, 1.0, v47
	v_rcp_f32_e32 v47, v47
	s_waitcnt lgkmcnt(0)
	v_mul_f32_e32 v46, v199, v46
	v_add_f32_e32 v186, 1.0, v50
	v_exp_f32_e32 v50, v46
	v_rcp_f32_e32 v46, v186
	v_fmamk_f32 v51, v51, 0xbfb8aa3b, v191
	v_mul_f32_e32 v47, v199, v47
	v_fma_f32 v186, -v50, v50, 1.0
	v_sqrt_f32_e32 v186, v186
	v_exp_f32_e32 v51, v51
	v_exp_f32_e32 v47, v47
	v_fmamk_f32 v48, v48, 0xbfb8aa3b, v190
	v_exp_f32_e32 v48, v48
	v_mul_f32_e32 v46, v46, v186
	v_add_f32_e32 v51, 1.0, v51
	v_fma_f32 v186, -v47, v47, 1.0
	v_rcp_f32_e32 v51, v51
	v_sqrt_f32_e32 v186, v186
	v_add_f32_e32 v48, 1.0, v48
	v_rcp_f32_e32 v48, v48
	v_fmamk_f32 v49, v49, 0xbfb8aa3b, v190
	v_mul_f32_e32 v51, v51, v186
	v_exp_f32_e32 v186, v49
	v_mul_f32_e32 v48, v199, v48
	v_exp_f32_e32 v49, v48
	v_fmamk_f32 v52, v52, 0xbfb8aa3b, v191
	v_add_f32_e32 v48, 1.0, v186
	v_rcp_f32_e32 v48, v48
	v_fmac_f32_e32 v191, 0xbfb8aa3b, v53
	v_exp_f32_e32 v189, v191
	v_exp_f32_e32 v52, v52
	v_mul_f32_e32 v48, v199, v48
	v_exp_f32_e32 v53, v48
	v_add_f32_e32 v48, 1.0, v189
	v_add_f32_e32 v52, 1.0, v52
	v_fma_f32 v186, -v49, v49, 1.0
	v_rcp_f32_e32 v189, v48
	v_fma_f32 v48, -v53, v53, 1.0
	v_rcp_f32_e32 v52, v52
	v_sqrt_f32_e32 v186, v186
	v_sqrt_f32_e32 v190, v48
	v_mul_f32_e32 v46, v46, v197
	v_mul_f32_e32 v48, v51, v195
	v_mul_f32_e32 v51, v52, v186
	v_mul_f32_e32 v52, v189, v190
	v_fma_f32 v189, 0, v50, v46
	v_lshlrev_b32_e32 v196, 16, v193
	v_mul_f32_e32 v51, v51, v194
	v_mul_f32_e32 v186, v50, v47
	v_fma_f32 v189, v47, v189, v48
	v_mul_f32_e32 v52, v52, v196
	v_mul_f32_e32 v186, v49, v186
	v_fma_f32 v189, v49, v189, v51
	v_mul_f32_e32 v186, v53, v186
	v_fma_f32 v189, v53, v189, v52
	v_mov_b32_e32 v192, v186
	v_mov_b32_e32 v190, v189
	s_nop 0
	v_permlane16_swap_b32_e32 v186, v192
	v_permlane16_swap_b32_e32 v189, v190
	v_mov_b32_e32 v193, v186
	v_mov_b32_e32 v191, v189
	s_nop 0
	v_permlane32_swap_b32_e32 v186, v193
	v_mov_b32_e32 v199, v192
	v_permlane32_swap_b32_e32 v189, v191
	v_mov_b32_e32 v200, v190
	v_permlane32_swap_b32_e32 v192, v199
	s_nop 0
	v_permlane32_swap_b32_e32 v190, v200
	v_fmac_f32_e32 v189, 0, v186
	v_fmac_f32_e32 v190, v189, v192
	v_mul_f32_e32 v192, v186, v192
	v_fmac_f32_e32 v191, v190, v193
	v_mul_f32_e32 v193, v192, v193
	s_and_saveexec_b64 s[28:29], s[10:11]
	v_mul_f32_e32 v201, v191, v199
	v_mul_f32_e32 v202, v193, v199
	v_add_f32_e32 v203, v201, v200
	ds_write_b64 v151, v[202:203] offset:52736
	s_or_b64 exec, exec, s[28:29]
	ds_read2st64_b32 v[198:199], v198 offset0:134 offset1:136
	ds_read_b32 v200, v122 offset:35456
	s_waitcnt lgkmcnt(1)
	v_fmamk_f32 v38, v38, 0xbfb8aa3b, v198
	v_exp_f32_e32 v38, v38
	v_fmamk_f32 v39, v39, 0xbfb8aa3b, v198
	v_exp_f32_e32 v39, v39
	v_fmamk_f32 v42, v42, 0xbfb8aa3b, v199
	v_add_f32_e32 v38, 1.0, v38
	v_rcp_f32_e32 v38, v38
	v_add_f32_e32 v39, 1.0, v39
	v_exp_f32_e32 v42, v42
	v_rcp_f32_e32 v39, v39
	s_waitcnt lgkmcnt(0)
	v_mul_f32_e32 v38, v200, v38
	v_exp_f32_e32 v38, v38
	v_fmamk_f32 v40, v40, 0xbfb8aa3b, v198
	v_fmamk_f32 v43, v43, 0xbfb8aa3b, v199
	v_add_f32_e32 v42, 1.0, v42
	v_mul_f32_e32 v39, v200, v39
	v_fma_f32 v201, -v38, v38, 1.0
	v_exp_f32_e32 v40, v40
	v_fmamk_f32 v41, v41, 0xbfb8aa3b, v198
	v_exp_f32_e32 v43, v43
	v_rcp_f32_e32 v42, v42
	v_exp_f32_e32 v39, v39
	v_sqrt_f32_e32 v201, v201
	v_exp_f32_e32 v41, v41
	v_add_f32_e32 v40, 1.0, v40
	v_add_f32_e32 v43, 1.0, v43
	v_fma_f32 v202, -v39, v39, 1.0
	v_mul_f32_e32 v42, v42, v201
	v_fmamk_f32 v44, v44, 0xbfb8aa3b, v199
	v_rcp_f32_e32 v40, v40
	v_add_f32_e32 v41, 1.0, v41
	v_rcp_f32_e32 v43, v43
	v_mul_f32_e32 v42, v42, v197
	v_sqrt_f32_e32 v197, v202
	v_exp_f32_e32 v44, v44
	v_rcp_f32_e32 v41, v41
	v_mul_f32_e32 v40, v200, v40
	v_fmac_f32_e32 v199, 0xbfb8aa3b, v45
	v_mul_f32_e32 v197, v43, v197
	v_add_f32_e32 v43, 1.0, v44
	v_exp_f32_e32 v40, v40
	v_exp_f32_e32 v45, v199
	v_mul_f32_e32 v41, v200, v41
	v_rcp_f32_e32 v44, v43
	v_exp_f32_e32 v43, v41
	v_fma_f32 v198, -v40, v40, 1.0
	v_add_f32_e32 v41, 1.0, v45
	v_sqrt_f32_e32 v198, v198
	v_rcp_f32_e32 v45, v41
	v_fma_f32 v41, -v43, v43, 1.0
	v_sqrt_f32_e32 v199, v41
	v_mul_f32_e32 v44, v44, v198
	v_mul_f32_e32 v44, v44, v194
	v_mul_f32_e32 v194, v43, v40
	v_mul_f32_e32 v45, v45, v199
	v_mul_f32_e32 v45, v45, v196
	v_mul_f32_e32 v194, v39, v194
	v_mul_f32_e32 v198, v38, v194
	v_fma_f32 v194, 0, v43, v45
	v_mul_f32_e32 v41, v197, v195
	v_fma_f32 v194, v40, v194, v44
	v_fma_f32 v194, v39, v194, v41
	v_fma_f32 v200, v38, v194, v42
	v_mov_b32_e32 v201, v198
	v_mov_b32_e32 v194, v200
	s_nop 0
	v_permlane16_swap_b32_e32 v198, v201
	v_permlane16_swap_b32_e32 v200, v194
	v_mov_b32_e32 v195, v201
	v_mov_b32_e32 v197, v194
	v_mov_b32_e32 v199, v198
	v_permlane32_swap_b32_e32 v201, v195
	v_mov_b32_e32 v196, v200
	v_permlane32_swap_b32_e32 v194, v197
	v_permlane32_swap_b32_e32 v198, v199
	v_permlane32_swap_b32_e32 v200, v196
	v_fmac_f32_e32 v197, 0, v195
	v_fmac_f32_e32 v196, v197, v199
	v_mul_f32_e32 v199, v199, v195
	v_fmac_f32_e32 v194, v196, v201
	v_mul_f32_e32 v201, v199, v201
	s_and_saveexec_b64 s[28:29], s[10:11]
	v_mul_f32_e32 v203, v194, v198
	v_mul_f32_e32 v202, v201, v198
	v_add_f32_e32 v203, v203, v200
	ds_write_b64 v151, v[202:203] offset:53248
	s_or_b64 exec, exec, s[28:29]
	v_add_u32_e32 v210, 0xc0, v122
	ds_read2st64_b32 v[202:203], v210 offset0:133 offset1:135
	ds_read_u16 v198, v142 offset:44544
	ds_read_u16 v200, v143 offset:44544
	ds_read_u16 v204, v144 offset:44544
	ds_read_u16 v205, v145 offset:44544
	ds_read_b32 v211, v122 offset:35264
	s_waitcnt lgkmcnt(4)
; template <bool PASS_C>
; DEVI void lru_item(const P& p, int item, int next_item, uint4& u0, uint4& u1, uint4& u2, float& cpre, char* smem) {
;     ...
;     float av[4][2][4], bv[4][2][4], apre[4][2], bpre[4][2];
; #pragma unroll
;     for (int nn = 0; nn < 4; ++nn) {
;         const int ch = 16 * nn + fr;
;         float uc[4];
; #pragma unroll
;         for (int j = 0; j < 4; ++j) {
;             const int tl = 16 * w + 4 * fq + j;
;             uc[j] = bf2f(*(const bf16_t*)(ucb + tl * 128 + ((((ch >> 3)) ^ (tl & 7)) << 4) + (ch & 7) * 2));
;         }
; #pragma unroll
;         for (int d = 0; d < 2; ++d) {
;             const float ba = prm[(5 + d) * 64 + ch], bx = prm[(7 + d) * 64 + ch], nsp8 = prm[(9 + d) * 64 + ch];
; #pragma unroll
;             for (int j = 0; j < 4; ++j) {
;                 const float r = __builtin_amdgcn_rcpf(1.0f + __builtin_amdgcn_exp2f(__builtin_fmaf(acc[(2 * d) * 4 + nn][j], -LOG2E, ba)));
;                 const float ig = __builtin_amdgcn_rcpf(1.0f + __builtin_amdgcn_exp2f(__builtin_fmaf(acc[(2 * d + 1) * 4 + nn][j], -LOG2E, bx)));
;                 const float a_ = __builtin_amdgcn_exp2f(nsp8 * r);
;                 av[nn][d][j] = a_;
;                 bv[nn][d][j] = __builtin_amdgcn_sqrtf(__builtin_fmaf(-a_, a_, 1.0f)) * ig * uc[j];
;             }
;             float A = 1.f, Bq = 0.f;
;             if (d == 0) {
; #pragma unroll
;                 for (int j = 0; j < 4; ++j) { Bq = av[nn][d][j] * Bq + bv[nn][d][j]; A *= av[nn][d][j]; }
;             } else {
; #pragma unroll
;                 for (int j = 3; j >= 0; --j) { Bq = av[nn][d][j] * Bq + bv[nn][d][j]; A *= av[nn][d][j]; }
;             }
;             float Ag[4], Bg[4];
;             rowgather4(A, Ag); rowgather4(Bq, Bg);
;             float AW = 1.f, BW = 0.f, AP = 1.f, BP = 0.f;
;             if (d == 0) {
; #pragma unroll
;                 for (int g = 0; g < 4; ++g) {
;                     if (g == fq) { AP = AW; BP = BW; }
;                     BW = Ag[g] * BW + Bg[g]; AW *= Ag[g];
;                 }
;             } else {
; #pragma unroll
;                 for (int g = 3; g >= 0; --g) {
;                     if (g == fq) { AP = AW; BP = BW; }
;                     BW = Ag[g] * BW + Bg[g]; AW *= Ag[g];
;                 }
;             }
;             apre[nn][d] = AP; bpre[nn][d] = BP;
	v_lshlrev_b32_e32 v209, 16, v198
	s_waitcnt lgkmcnt(3)
	v_lshlrev_b32_e32 v207, 16, v200
	s_waitcnt lgkmcnt(2)
	v_lshlrev_b32_e32 v206, 16, v204
	v_fmamk_f32 v30, v30, 0xbfb8aa3b, v202
	v_exp_f32_e32 v30, v30
	v_fmamk_f32 v31, v31, 0xbfb8aa3b, v202
	v_fmamk_f32 v34, v34, 0xbfb8aa3b, v203
	v_exp_f32_e32 v31, v31
	v_add_f32_e32 v30, 1.0, v30
	v_rcp_f32_e32 v30, v30
	v_exp_f32_e32 v34, v34
	v_add_f32_e32 v31, 1.0, v31
	v_rcp_f32_e32 v31, v31
	s_waitcnt lgkmcnt(0)
	v_mul_f32_e32 v30, v211, v30
	v_add_f32_e32 v198, 1.0, v34
	v_exp_f32_e32 v34, v30
	v_rcp_f32_e32 v30, v198
	v_fmamk_f32 v35, v35, 0xbfb8aa3b, v203
	v_mul_f32_e32 v31, v211, v31
	v_fma_f32 v198, -v34, v34, 1.0
	v_sqrt_f32_e32 v198, v198
	v_exp_f32_e32 v35, v35
	v_exp_f32_e32 v31, v31
	v_fmamk_f32 v32, v32, 0xbfb8aa3b, v202
	v_exp_f32_e32 v32, v32
	v_mul_f32_e32 v30, v30, v198
	v_add_f32_e32 v35, 1.0, v35
	v_fma_f32 v198, -v31, v31, 1.0
	v_rcp_f32_e32 v35, v35
	v_sqrt_f32_e32 v198, v198
	v_add_f32_e32 v32, 1.0, v32
	v_rcp_f32_e32 v32, v32
	v_fmamk_f32 v33, v33, 0xbfb8aa3b, v202
	v_mul_f32_e32 v35, v35, v198
	v_exp_f32_e32 v198, v33
	v_mul_f32_e32 v32, v211, v32
	v_exp_f32_e32 v33, v32
	v_fmamk_f32 v36, v36, 0xbfb8aa3b, v203
	v_add_f32_e32 v32, 1.0, v198
	v_rcp_f32_e32 v32, v32
	v_fmac_f32_e32 v203, 0xbfb8aa3b, v37
	v_exp_f32_e32 v200, v203
	v_exp_f32_e32 v36, v36
	v_mul_f32_e32 v32, v211, v32
	v_exp_f32_e32 v37, v32
	v_add_f32_e32 v32, 1.0, v200
	v_add_f32_e32 v36, 1.0, v36
	v_fma_f32 v198, -v33, v33, 1.0
	v_rcp_f32_e32 v200, v32
	v_fma_f32 v32, -v37, v37, 1.0
	v_rcp_f32_e32 v36, v36
	v_sqrt_f32_e32 v198, v198
	v_sqrt_f32_e32 v202, v32
	v_mul_f32_e32 v30, v30, v209
	v_mul_f32_e32 v32, v35, v207
	v_mul_f32_e32 v35, v36, v198
	v_mul_f32_e32 v36, v200, v202
	v_fma_f32 v200, 0, v34, v30
	v_lshlrev_b32_e32 v208, 16, v205
	v_mul_f32_e32 v35, v35, v206
	v_mul_f32_e32 v198, v34, v31
	v_fma_f32 v200, v31, v200, v32
	v_mul_f32_e32 v36, v36, v208
	v_mul_f32_e32 v198, v33, v198
	v_fma_f32 v200, v33, v200, v35
	v_mul_f32_e32 v198, v37, v198
	v_fma_f32 v200, v37, v200, v36
	v_mov_b32_e32 v204, v198
	v_mov_b32_e32 v202, v200
	s_nop 0
	v_permlane16_swap_b32_e32 v198, v204
	v_permlane16_swap_b32_e32 v200, v202
	v_mov_b32_e32 v205, v198
	v_mov_b32_e32 v203, v200
	s_nop 0
	v_permlane32_swap_b32_e32 v198, v205
	v_mov_b32_e32 v211, v204
	v_permlane32_swap_b32_e32 v200, v203
	v_mov_b32_e32 v212, v202
	v_permlane32_swap_b32_e32 v204, v211
	s_nop 0
	v_permlane32_swap_b32_e32 v202, v212
	v_fmac_f32_e32 v200, 0, v198
	v_fmac_f32_e32 v202, v200, v204
	v_mul_f32_e32 v204, v198, v204
	v_fmac_f32_e32 v203, v202, v205
	v_mul_f32_e32 v205, v204, v205
	s_and_saveexec_b64 s[28:29], s[10:11]
	v_mul_f32_e32 v213, v203, v211
	v_mul_f32_e32 v214, v205, v211
	v_add_f32_e32 v215, v213, v212
	ds_write_b64 v152, v[214:215] offset:52736
	s_or_b64 exec, exec, s[28:29]
	ds_read2st64_b32 v[210:211], v210 offset0:134 offset1:136
	ds_read_b32 v212, v122 offset:35520
	s_waitcnt lgkmcnt(1)
	v_fmamk_f32 v22, v22, 0xbfb8aa3b, v210
	v_exp_f32_e32 v22, v22
	v_fmamk_f32 v23, v23, 0xbfb8aa3b, v210
	v_exp_f32_e32 v23, v23
	v_fmamk_f32 v26, v26, 0xbfb8aa3b, v211
	v_add_f32_e32 v22, 1.0, v22
	v_rcp_f32_e32 v22, v22
	v_add_f32_e32 v23, 1.0, v23
	v_exp_f32_e32 v26, v26
	v_rcp_f32_e32 v23, v23
	s_waitcnt lgkmcnt(0)
	v_mul_f32_e32 v22, v212, v22
	v_exp_f32_e32 v22, v22
	v_fmamk_f32 v24, v24, 0xbfb8aa3b, v210
	v_fmamk_f32 v27, v27, 0xbfb8aa3b, v211
	v_add_f32_e32 v26, 1.0, v26
	v_mul_f32_e32 v23, v212, v23
	v_fma_f32 v213, -v22, v22, 1.0
	v_exp_f32_e32 v24, v24
	v_fmamk_f32 v25, v25, 0xbfb8aa3b, v210
	v_exp_f32_e32 v27, v27
	v_rcp_f32_e32 v26, v26
	v_exp_f32_e32 v23, v23
	v_sqrt_f32_e32 v213, v213
	v_exp_f32_e32 v25, v25
	v_add_f32_e32 v24, 1.0, v24
	v_add_f32_e32 v27, 1.0, v27
	v_fma_f32 v214, -v23, v23, 1.0
	v_mul_f32_e32 v26, v26, v213
	v_fmamk_f32 v28, v28, 0xbfb8aa3b, v211
	v_rcp_f32_e32 v24, v24
	v_add_f32_e32 v25, 1.0, v25
	v_rcp_f32_e32 v27, v27
	v_mul_f32_e32 v26, v26, v209
	v_sqrt_f32_e32 v209, v214
	v_exp_f32_e32 v28, v28
	v_rcp_f32_e32 v25, v25
	v_mul_f32_e32 v24, v212, v24
	v_fmac_f32_e32 v211, 0xbfb8aa3b, v29
	v_mul_f32_e32 v209, v27, v209
	v_add_f32_e32 v27, 1.0, v28
	v_exp_f32_e32 v24, v24
	v_exp_f32_e32 v29, v211
	v_mul_f32_e32 v25, v212, v25
	v_rcp_f32_e32 v28, v27
	v_exp_f32_e32 v27, v25
	v_fma_f32 v210, -v24, v24, 1.0
	v_add_f32_e32 v25, 1.0, v29
	v_sqrt_f32_e32 v210, v210
	v_rcp_f32_e32 v29, v25
	v_fma_f32 v25, -v27, v27, 1.0
	v_sqrt_f32_e32 v211, v25
	v_mul_f32_e32 v28, v28, v210
	v_mul_f32_e32 v28, v28, v206
	v_mul_f32_e32 v206, v27, v24
	v_mul_f32_e32 v29, v29, v211
	v_mul_f32_e32 v29, v29, v208
	v_mul_f32_e32 v206, v23, v206
	v_mul_f32_e32 v212, v22, v206
	v_fma_f32 v206, 0, v27, v29
	v_mul_f32_e32 v25, v209, v207
	v_fma_f32 v206, v24, v206, v28
	v_fma_f32 v206, v23, v206, v25
	v_fma_f32 v213, v22, v206, v26
	v_mov_b32_e32 v211, v212
	v_mov_b32_e32 v207, v213
	s_nop 0
	v_permlane16_swap_b32_e32 v212, v211
	v_permlane16_swap_b32_e32 v213, v207
	v_mov_b32_e32 v206, v211
	v_mov_b32_e32 v209, v207
	v_mov_b32_e32 v210, v212
	v_permlane32_swap_b32_e32 v211, v206
	v_mov_b32_e32 v208, v213
	v_permlane32_swap_b32_e32 v207, v209
	v_permlane32_swap_b32_e32 v212, v210
	v_permlane32_swap_b32_e32 v213, v208
	v_fmac_f32_e32 v209, 0, v206
	v_fmac_f32_e32 v208, v209, v210
	v_mul_f32_e32 v210, v210, v206
	v_fmac_f32_e32 v207, v208, v211
	v_mul_f32_e32 v211, v210, v211
	s_and_saveexec_b64 s[28:29], s[10:11]
	v_mul_f32_e32 v214, v207, v212
	v_mul_f32_e32 v212, v211, v212
	v_add_f32_e32 v213, v214, v213
	ds_write_b64 v152, v[212:213] offset:53248
	s_or_b64 exec, exec, s[28:29]
	s_waitcnt lgkmcnt(0)
	s_barrier
; template <bool PASS_C>
; DEVI void lru_item(const P& p, int item, int next_item, uint4& u0, uint4& u1, uint4& u2, float& cpre, char* smem) {
;     ...
; #pragma unroll
;         for (int nn = 0; nn < 4; ++nn) {
;             const int ch = 16 * nn + fr;
;             float y[4];
;             {
;                 float hw = carry[ch];
; #pragma unroll
;                 for (int ww = 0; ww < 4; ++ww)
;                     if (ww < w) hw = wagg[((ww * 2 + 0) * 64 + ch) * 2] * hw + wagg[((ww * 2 + 0) * 64 + ch) * 2 + 1];
;                 float hh = apre[nn][0] * hw + bpre[nn][0];
; #pragma unroll
;                 for (int j = 0; j < 4; ++j) { hh = av[nn][0][j] * hh + bv[nn][0][j]; y[j] = hh; }
;             }
;             {
;                 float hw = carry[64 + ch];
; #pragma unroll
;     ...
;                     if (ww > w) hw = wagg[((ww * 2 + 1) * 64 + ch) * 2] * hw + wagg[((ww * 2 + 1) * 64 + ch) * 2 + 1];
;                 float hh = apre[nn][1] * hw + bpre[nn][1];
; #pragma unroll
;                 for (int j = 3; j >= 0; --j) { hh = av[nn][1][j] * hh + bv[nn][1][j]; y[j] += hh; }
;             }
; #pragma unroll
;             for (int j = 0; j < 4; ++j) ytile[(16 * w + 4 * fq + j) * 66 + ch] = y[j];
;         }
	ds_read_b32 v244, v122 offset:56832
	ds_read_b32 v245, v122 offset:57088
	ds_read_b64 v[232:233], v123 offset:52736
	ds_read_b64 v[234:235], v123 offset:53760
	ds_read_b64 v[236:237], v123 offset:54784
	ds_read_b64 v[238:239], v123 offset:56320
	ds_read_b64 v[240:241], v123 offset:55296
	ds_read_b64 v[242:243], v123 offset:54272
	ds_read_b32 v246, v122 offset:56896
	ds_read_b32 v247, v122 offset:57152
	ds_read_b64 v[218:219], v154 offset:52736
	ds_read_b64 v[220:221], v154 offset:53760
	ds_read_b64 v[222:223], v154 offset:54784
	ds_read_b64 v[224:225], v154 offset:56320
	ds_read_b64 v[226:227], v154 offset:55296
	ds_read_b64 v[228:229], v154 offset:54272
	s_waitcnt lgkmcnt(8)
	v_fma_f32 v248, v232, v244, v233
	v_cndmask_b32_e64 v212, v244, v248, s[4:5]
	v_fma_f32 v248, v234, v212, v235
	v_cndmask_b32_e64 v212, v212, v248, s[18:19]
	v_fma_f32 v248, v236, v212, v237
	v_cndmask_b32_e64 v212, v212, v248, s[20:21]
	v_fma_f32 v248, v238, v245, v239
	v_cndmask_b32_e64 v213, v245, v248, s[24:25]
	v_fma_f32 v248, v240, v213, v241
	v_cndmask_b32_e64 v213, v213, v248, s[8:9]
	v_fma_f32 v248, v242, v213, v243
	v_cndmask_b32_e64 v213, v213, v248, s[2:3]
	v_cndmask_b32_e64 v103, 1.0, v103, s[12:13]
	v_cndmask_b32_e64 v105, 0, v105, s[12:13]
	v_cndmask_b32_e64 v103, v103, v159, s[14:15]
	v_cndmask_b32_e64 v105, v105, v157, s[14:15]
	v_cndmask_b32_e64 v103, v103, v160, s[16:17]
	v_cndmask_b32_e64 v105, v105, v158, s[16:17]
	v_fmac_f32_e32 v105, v103, v212
	v_fmac_f32_e32 v87, v89, v105
	v_fmac_f32_e32 v93, v91, v87
	v_cndmask_b32_e64 v89, 1.0, v162, s[14:15]
	v_cndmask_b32_e64 v91, 0, v164, s[14:15]
	v_cndmask_b32_e64 v89, v89, v166, s[12:13]
	v_cndmask_b32_e64 v91, v91, v163, s[12:13]
	v_cndmask_b32_e64 v89, v89, v167, s[10:11]
	v_cndmask_b32_e64 v91, v91, v161, s[10:11]
	v_fmac_f32_e32 v91, v89, v213
	v_fmac_f32_e32 v77, v75, v91
	v_fmac_f32_e32 v76, v72, v77
	v_fmac_f32_e32 v73, v71, v76
	v_fmac_f32_e32 v97, v95, v93
	v_fmac_f32_e32 v74, v70, v73
	v_fmac_f32_e32 v99, v101, v97
	v_add_f32_e32 v71, v93, v73
	v_add_f32_e32 v73, v87, v74
	v_add_u32_e32 v70, 0x8c00, v153
	v_add_f32_e32 v75, v99, v77
	v_add_f32_e32 v72, v97, v76
	ds_write2_b32 v70, v73, v71 offset1:66
	ds_write2_b32 v70, v72, v75 offset0:132 offset1:198
	ds_read_b32 v244, v122 offset:56960
	ds_read_b32 v245, v122 offset:57216
	ds_read_b64 v[232:233], v155 offset:52736
	ds_read_b64 v[234:235], v155 offset:53760
	ds_read_b64 v[236:237], v155 offset:54784
	ds_read_b64 v[238:239], v155 offset:56320
	ds_read_b64 v[240:241], v155 offset:55296
	ds_read_b64 v[242:243], v155 offset:54272
	s_waitcnt lgkmcnt(10)
	v_fma_f32 v248, v218, v246, v219
	v_cndmask_b32_e64 v71, v246, v248, s[4:5]
	v_fma_f32 v248, v220, v71, v221
	v_cndmask_b32_e64 v71, v71, v248, s[18:19]
	v_fma_f32 v248, v222, v71, v223
	v_cndmask_b32_e64 v71, v71, v248, s[20:21]
	v_fma_f32 v248, v224, v247, v225
	v_cndmask_b32_e64 v72, v247, v248, s[24:25]
	v_fma_f32 v248, v226, v72, v227
	v_cndmask_b32_e64 v72, v72, v248, s[8:9]
	v_fma_f32 v248, v228, v72, v229
	v_cndmask_b32_e64 v72, v72, v248, s[2:3]
	v_cndmask_b32_e64 v73, 1.0, v165, s[12:13]
	v_cndmask_b32_e64 v74, 0, v168, s[12:13]
	v_cndmask_b32_e64 v73, v73, v171, s[14:15]
	v_cndmask_b32_e64 v74, v74, v169, s[14:15]
	v_cndmask_b32_e64 v73, v73, v173, s[16:17]
	v_cndmask_b32_e64 v74, v74, v170, s[16:17]
	v_fmac_f32_e32 v74, v73, v71
	v_fmac_f32_e32 v62, v66, v74
	v_fmac_f32_e32 v64, v63, v62
	v_fmac_f32_e32 v67, v65, v64
	v_cndmask_b32_e64 v63, 1.0, v183, s[14:15]
	v_cndmask_b32_e64 v65, 0, v185, s[14:15]
	v_cndmask_b32_e64 v63, v63, v187, s[12:13]
	v_cndmask_b32_e64 v65, v65, v184, s[12:13]
	v_cndmask_b32_e64 v63, v63, v188, s[10:11]
	v_cndmask_b32_e64 v65, v65, v177, s[10:11]
	v_fmac_f32_e32 v65, v63, v72
	v_fmac_f32_e32 v61, v59, v65
	v_fmac_f32_e32 v60, v56, v61
	v_fmac_f32_e32 v57, v55, v60
	v_fmac_f32_e32 v58, v54, v57
	v_fmac_f32_e32 v68, v69, v67
	v_add_f32_e32 v55, v64, v57
	v_add_f32_e32 v54, v62, v58
	v_add_f32_e32 v59, v68, v61
	v_add_f32_e32 v56, v67, v60
	ds_write2_b32 v70, v54, v55 offset0:16 offset1:82
	ds_write2_b32 v70, v56, v59 offset0:148 offset1:214
	ds_read_b32 v246, v122 offset:57024
	ds_read_b32 v247, v122 offset:57280
	ds_read_b64 v[218:219], v156 offset:52736
	ds_read_b64 v[220:221], v156 offset:53760
	ds_read_b64 v[222:223], v156 offset:54784
	ds_read_b64 v[224:225], v156 offset:56320
	ds_read_b64 v[226:227], v156 offset:55296
	ds_read_b64 v[228:229], v156 offset:54272
	s_waitcnt lgkmcnt(10)
	v_fma_f32 v248, v232, v244, v233
	v_cndmask_b32_e64 v54, v244, v248, s[4:5]
	v_fma_f32 v248, v234, v54, v235
	v_cndmask_b32_e64 v54, v54, v248, s[18:19]
	v_fma_f32 v248, v236, v54, v237
	v_cndmask_b32_e64 v54, v54, v248, s[20:21]
	v_fma_f32 v248, v238, v245, v239
	v_cndmask_b32_e64 v55, v245, v248, s[24:25]
	v_fma_f32 v248, v240, v55, v241
	v_cndmask_b32_e64 v55, v55, v248, s[8:9]
	v_fma_f32 v248, v242, v55, v243
	v_cndmask_b32_e64 v55, v55, v248, s[2:3]
	v_cndmask_b32_e64 v56, 1.0, v186, s[12:13]
	v_cndmask_b32_e64 v57, 0, v189, s[12:13]
	v_cndmask_b32_e64 v56, v56, v192, s[14:15]
	v_cndmask_b32_e64 v57, v57, v190, s[14:15]
	v_cndmask_b32_e64 v56, v56, v193, s[16:17]
	v_cndmask_b32_e64 v57, v57, v191, s[16:17]
	v_fmac_f32_e32 v57, v56, v54
	v_fmac_f32_e32 v46, v50, v57
	v_fmac_f32_e32 v48, v47, v46
	v_fmac_f32_e32 v51, v49, v48
	v_cndmask_b32_e64 v47, 1.0, v195, s[14:15]
	v_cndmask_b32_e64 v49, 0, v197, s[14:15]
	v_cndmask_b32_e64 v47, v47, v199, s[12:13]
	v_cndmask_b32_e64 v49, v49, v196, s[12:13]
	v_cndmask_b32_e64 v47, v47, v201, s[10:11]
	v_cndmask_b32_e64 v49, v49, v194, s[10:11]
	v_fmac_f32_e32 v49, v47, v55
	v_fmac_f32_e32 v45, v43, v49
	v_fmac_f32_e32 v44, v40, v45
	v_fmac_f32_e32 v41, v39, v44
	v_fmac_f32_e32 v42, v38, v41
	v_fmac_f32_e32 v52, v53, v51
	v_add_f32_e32 v39, v48, v41
	v_add_f32_e32 v38, v46, v42
	v_add_f32_e32 v43, v52, v45
	v_add_f32_e32 v40, v51, v44
	ds_write2_b32 v70, v38, v39 offset0:32 offset1:98
	ds_write2_b32 v70, v40, v43 offset0:164 offset1:230
	s_waitcnt lgkmcnt(2)
	v_fma_f32 v248, v218, v246, v219
	v_cndmask_b32_e64 v38, v246, v248, s[4:5]
	v_fma_f32 v248, v220, v38, v221
	v_cndmask_b32_e64 v38, v38, v248, s[18:19]
	v_fma_f32 v248, v222, v38, v223
	v_cndmask_b32_e64 v38, v38, v248, s[20:21]
	v_fma_f32 v248, v224, v247, v225
	v_cndmask_b32_e64 v39, v247, v248, s[24:25]
	v_fma_f32 v248, v226, v39, v227
	v_cndmask_b32_e64 v39, v39, v248, s[8:9]
	v_fma_f32 v248, v228, v39, v229
	v_cndmask_b32_e64 v39, v39, v248, s[2:3]
	s_branch .LBB0_720

; DEVI unsigned pk2(float lo, float hi) { f32x2 v = {lo, hi}; bf16x2_t b = __builtin_convertvector(v, bf16x2_t); return __builtin_bit_cast(unsigned, b); }
; DEVI float bflo(unsigned u) { return __uint_as_float(u << 16); }
; DEVI float bfhi(unsigned u) { return __uint_as_float(u & 0xffff0000u); }
; template <bool PASS_C>
; DEVI void lru_item(const P& p, int item, int next_item, uint4& u0, uint4& u1, uint4& u2, float& cpre, char* smem) {
;     ...
;                 float hh = apre[nn][0] * hw + bpre[nn][0];
; #pragma unroll
;                 for (int j = 0; j < 4; ++j) { hh = av[nn][0][j] * hh + bv[nn][0][j]; y[j] = hh; }
;             }
;             {
;                 float hw = carry[64 + ch];
; #pragma unroll
;     ...
;                     if (ww > w) hw = wagg[((ww * 2 + 1) * 64 + ch) * 2] * hw + wagg[((ww * 2 + 1) * 64 + ch) * 2 + 1];
;                 float hh = apre[nn][1] * hw + bpre[nn][1];
; #pragma unroll
;                 for (int j = 3; j >= 0; --j) { hh = av[nn][1][j] * hh + bv[nn][1][j]; y[j] += hh; }
;             }
; #pragma unroll
;             for (int j = 0; j < 4; ++j) ytile[(16 * w + 4 * fq + j) * 66 + ch] = y[j];
;         }
;         __syncthreads();
;         {
;             const int tok = tid >> 2, cg0 = (tid & 3) * 16;
;             bf16_t* MX = (bf16_t*)(p.ws + OFF_A) + (rbase + tb + tok) * 1024 + h * 64 + cg0;
; #pragma unroll
;             for (int i = 0; i < 2; ++i) {
;                 const uint4 s = i ? sg1 : sg0;
;                 const float* yy = ytile + tok * 66 + cg0 + 8 * i;
;                 uint4 o;
;                 o.x = pk2(yy[0] * bflo(s.x), yy[1] * bfhi(s.x)); o.y = pk2(yy[2] * bflo(s.y), yy[3] * bfhi(s.y));
;                 o.z = pk2(yy[4] * bflo(s.z), yy[5] * bfhi(s.z)); o.w = pk2(yy[6] * bflo(s.w), yy[7] * bfhi(s.w));
;                 *(uint4*)(MX + 8 * i) = o;
;             }
;         }
.LBB0_1043:
	s_or_b64 exec, exec, s[28:29]
	v_cndmask_b32_e64 v40, 1.0, v198, s[12:13]
	v_cndmask_b32_e64 v41, 0, v200, s[12:13]
	v_cndmask_b32_e64 v40, v40, v204, s[14:15]
	v_cndmask_b32_e64 v41, v41, v202, s[14:15]
	v_cndmask_b32_e64 v40, v40, v205, s[16:17]
	v_cndmask_b32_e64 v41, v41, v203, s[16:17]
	v_fmac_f32_e32 v41, v40, v38
	v_fmac_f32_e32 v30, v34, v41
	v_fmac_f32_e32 v32, v31, v30
	v_fmac_f32_e32 v35, v33, v32
	v_cndmask_b32_e64 v31, 0, v209, s[14:15]
	v_cndmask_b32_e64 v33, 1.0, v206, s[14:15]
	v_cndmask_b32_e64 v31, v31, v208, s[12:13]
	v_cndmask_b32_e64 v33, v33, v210, s[12:13]
	v_cndmask_b32_e64 v31, v31, v207, s[10:11]
	v_cndmask_b32_e64 v33, v33, v211, s[10:11]
	v_fmac_f32_e32 v31, v33, v39
	v_fmac_f32_e32 v29, v27, v31
	v_fmac_f32_e32 v28, v24, v29
	v_fmac_f32_e32 v25, v23, v28
	v_fmac_f32_e32 v26, v22, v25
	v_fmac_f32_e32 v36, v37, v35
	v_add_f32_e32 v23, v32, v25
	v_add_f32_e32 v22, v30, v26
	v_add_f32_e32 v27, v36, v29
	v_add_f32_e32 v24, v35, v28
	ds_write2_b32 v70, v22, v23 offset0:48 offset1:114
	ds_write2_b32 v70, v24, v27 offset0:180 offset1:246
	v_lshl_add_u64 v[22:23], v[106:107], 1, s[90:91]
	v_lshl_add_u64 v[22:23], v[22:23], 0, s[0:1]
	v_lshl_add_u64 v[30:31], v[22:23], 0, v[78:79]
	v_add_u32_e32 v22, 0x8c00, v124
	s_waitcnt lgkmcnt(0)
	s_barrier
	ds_read2_b64 v[22:25], v22 offset1:1
	s_waitcnt vmcnt(0)
	v_lshlrev_b32_e32 v32, 16, v18
	v_and_b32_e32 v33, 0xffff0000, v18
	v_add_u32_e32 v18, 0x8c10, v124
	ds_read2_b64 v[26:29], v18 offset1:1
	s_waitcnt lgkmcnt(1)
	v_pk_mul_f32 v[22:23], v[22:23], v[32:33]
	s_add_i32 s34, s34, s35
	v_cvt_pk_bf16_f32 v18, v22, v23
	v_lshlrev_b32_e32 v22, 16, v19
	v_and_b32_e32 v23, 0xffff0000, v19
	v_pk_mul_f32 v[22:23], v[24:25], v[22:23]
	s_and_b64 vcc, exec, s[30:31]
	v_cvt_pk_bf16_f32 v19, v22, v23
	v_lshlrev_b32_e32 v22, 16, v20
	v_and_b32_e32 v23, 0xffff0000, v20
	s_waitcnt lgkmcnt(0)
	v_pk_mul_f32 v[22:23], v[26:27], v[22:23]
	v_lshlrev_b32_e32 v26, 16, v14
	v_cvt_pk_bf16_f32 v20, v22, v23
	v_lshlrev_b32_e32 v22, 16, v21
	v_and_b32_e32 v23, 0xffff0000, v21
	v_pk_mul_f32 v[22:23], v[28:29], v[22:23]
	v_and_b32_e32 v27, 0xffff0000, v14
	v_cvt_pk_bf16_f32 v21, v22, v23
	global_store_dwordx4 v[30:31], v[18:21], off
	v_add_u32_e32 v14, 0x8c30, v124
	ds_read2_b64 v[22:25], v14 offset1:1
	v_add_u32_e32 v18, 0x8c20, v124
	ds_read2_b64 v[18:21], v18 offset1:1
	s_mov_b32 s33, s51
	s_waitcnt lgkmcnt(0)
	v_pk_mul_f32 v[18:19], v[18:19], v[26:27]
	s_nop 0
	v_cvt_pk_bf16_f32 v14, v18, v19
	v_lshlrev_b32_e32 v18, 16, v15
	v_and_b32_e32 v19, 0xffff0000, v15
	v_pk_mul_f32 v[18:19], v[20:21], v[18:19]
	s_nop 0
	v_cvt_pk_bf16_f32 v15, v18, v19
	v_lshlrev_b32_e32 v18, 16, v16
	v_and_b32_e32 v19, 0xffff0000, v16
	v_pk_mul_f32 v[18:19], v[22:23], v[18:19]
	s_nop 0
	v_cvt_pk_bf16_f32 v16, v18, v19
	v_lshlrev_b32_e32 v18, 16, v17
	v_and_b32_e32 v19, 0xffff0000, v17
	v_pk_mul_f32 v[18:19], v[24:25], v[18:19]
	s_nop 0
	v_cvt_pk_bf16_f32 v17, v18, v19
	global_store_dwordx4 v[30:31], v[14:17], off offset:16
	s_cbranch_vccnz .LBB0_1134
